# residual GEMM epilogue: h/gate loads issued in bulk (16 in flight) instead of a 32-step load-wait-store ladder; plus batched ctx partial loads in norm phases
# speedup vs baseline: 1.0210x; 1.0180x over previous
;     __device__ bool next(int i, Unit& u) const { if (i > 0 || !has) return false; u.pm = pm; u.pn = pn; return true; }
; template <class Epi, class Sched>
; __device__ __forceinline__ void gemm_phase(LAS unsigned char* lds, const Gemm g, const Sched& S, const Epi& E) {
;     ...
;         const bool has_next = S.next(ui + 1, nxt);
;         const char* nA = has_next ? (const char*)g.A + (size_t)nxt.pm * tstepA : cA; const char* nB = has_next ? (const char*)g.Bt + (size_t)nxt.pn * tstepB : cB;
;     ...
;         if (!has_next) break;
; #pragma unroll
;         for (int a = 0; a < 2; ++a)
; #pragma unroll
;             for (int b = 0; b < 2; ++b)
; #pragma unroll
;                 for (int m = 0; m < 4; ++m)
; #pragma unroll
;                     for (int n = 0; n < 2; ++n) acc[a][b][m][n] = (f32x4){0.f, 0.f, 0.f, 0.f};
;         cur = nxt; cA = nA; cB = nB; ++ui;
.LBB0_555:
	s_and_b64 vcc, exec, s[4:5]
	s_mov_b32 s58, s49
	s_mov_b64 s[2:3], s[8:9]
	s_mov_b64 s[24:25], s[6:7]
	s_mov_b32 s13, s48
	s_cbranch_vccnz .LBB0_600

; #define PG8_STAGE(bufoff, gbase, voff) do { _Pragma("unroll") for (int _i = 0; _i < 2; ++_i) \
;         __builtin_amdgcn_global_load_lds((const unsigned*)((const char*)(gbase) + (voff)[_i]), (LAS unsigned*)(lds + (bufoff) + ldsw + _i * 8192), 16, 0, 0); } while (0)
; #define PG8_LDA(dst, b, h) do { _Pragma("unroll") for (int m = 0; m < 4; ++m) _Pragma("unroll") for (int k = 0; k < 2; ++k) dst[m][k] = *(const LAS bf16x8*)(lds + PG8_SA(b, h) + aoff + m * 2048 + k * 1024); } while (0)
; #define PG8_LDB(dst, b, h) do { _Pragma("unroll") for (int n = 0; n < 2; ++n) _Pragma("unroll") for (int k = 0; k < 2; ++k) dst[n][k] = *(const LAS bf16x8*)(lds + PG8_SB(b, h) + boff + n * 2048 + k * 1024); } while (0)
; #define PG8_MMA(ai, bj, At, Bt) do { __builtin_amdgcn_s_setprio(1); _Pragma("unroll") for (int m = 0; m < 4; ++m) _Pragma("unroll") for (int n = 0; n < 2; ++n) _Pragma("unroll") for (int k = 0; k < 2; ++k) \
;         acc[ai][bj][m][n] = __builtin_amdgcn_mfma_f32_16x16x32_bf16(Bt[n][k], At[m][k], acc[ai][bj][m][n], 0, 0, 0); __builtin_amdgcn_s_setprio(0); } while (0)
; #define PG8_WAIT_L(n) asm volatile("s_waitcnt lgkmcnt(" #n ")" ::: "memory")
; #define PG8_BAR __builtin_amdgcn_s_barrier()
; #define PG8_SCHED __builtin_amdgcn_sched_barrier(0)
; template <class Epi, class Sched>
; __device__ __forceinline__ void gemm_phase(LAS unsigned char* lds, const Gemm g, const Sched& S, const Epi& E) {
;     ...
;             PG8_LDB(B0, 0, 0); PG8_SCHED; PG8_LDA(At, 0, 0); PG8_STAGE(PG8_SA(1, 1), a1 + hstepA, voffA);
;             PG8_WAIT_L(8); PG8_BAR; PG8_WAIT_L(0); PG8_MMA(0, 0, At, B0); PG8_BAR; PG8_SCHED;
;             PG8_LDB(B1, 0, 1); PG8_STAGE(PG8_SB(0, 0), b2, voffB);
;             PG8_BAR; PG8_WAIT_L(0); PG8_MMA(0, 1, At, B1); PG8_BAR;
;             PG8_LDA(At, 0, 1); PG8_STAGE(PG8_SA(0, 0), a2, voffA);
;             PG8_BAR; PG8_WAIT_L(0); PG8_MMA(1, 0, At, B0); PG8_BAR; PG8_SCHED;
.LBB0_567:
	s_add_i32 s61, s0, 2
	s_add_u32 s1, s2, 0x80
	s_addc_u32 s24, s3, 0
	s_add_i32 s62, 0, 0x10000
	v_add_u32_e32 v147, s62, v1
	ds_read_b128 v[138:141], v147
	ds_read_b128 v[142:145], v147 offset:1024
	ds_read_b128 v[148:151], v147 offset:2048
	ds_read_b128 v[152:155], v147 offset:3072
	s_cmp_eq_u32 s44, s0
	s_cselect_b32 s0, s8, s59
	s_cselect_b32 s25, s7, s24
	s_cselect_b32 s24, s6, s1
	s_cselect_b32 s1, s9, s60
	v_lshl_add_u64 v[190:191], s[2:3], 0, v[136:137]
	s_add_i32 m0, s37, 0xc000
	ds_read_b128 v[156:159], v146
	ds_read_b128 v[160:163], v146 offset:1024
	ds_read_b128 v[164:167], v146 offset:2048
	ds_read_b128 v[168:171], v146 offset:3072
	ds_read_b128 v[172:175], v146 offset:4096
	ds_read_b128 v[176:179], v146 offset:5120
	ds_read_b128 v[180:183], v146 offset:6144
	ds_read_b128 v[184:187], v146 offset:7168
	global_load_lds_dwordx4 v[190:191], off
	v_lshl_add_u64 v[190:191], s[2:3], 0, v[134:135]
	s_add_i32 m0, s37, 0xe000
	s_nop 0
	global_load_lds_dwordx4 v[190:191], off
	s_waitcnt lgkmcnt(8)
	s_barrier
	s_waitcnt lgkmcnt(0)
	s_setprio 1
	s_waitcnt lgkmcnt(0)
	v_mfma_f32_16x16x32_bf16 v[126:129], v[138:141], v[156:159], v[126:129]
	v_mfma_f32_16x16x32_bf16 v[122:125], v[148:151], v[156:159], v[122:125]
	v_mfma_f32_16x16x32_bf16 v[110:113], v[138:141], v[164:167], v[110:113]
	v_mfma_f32_16x16x32_bf16 v[106:109], v[148:151], v[164:167], v[106:109]
	v_mfma_f32_16x16x32_bf16 v[94:97], v[138:141], v[172:175], v[94:97]
	v_mfma_f32_16x16x32_bf16 v[90:93], v[148:151], v[172:175], v[90:93]
	v_mfma_f32_16x16x32_bf16 v[78:81], v[138:141], v[180:183], v[78:81]
	v_mfma_f32_16x16x32_bf16 v[74:77], v[148:151], v[180:183], v[74:77]
	v_mfma_f32_16x16x32_bf16 v[126:129], v[142:145], v[160:163], v[126:129]
	v_mfma_f32_16x16x32_bf16 v[122:125], v[152:155], v[160:163], v[122:125]
	v_mfma_f32_16x16x32_bf16 v[110:113], v[142:145], v[168:171], v[110:113]
	v_mfma_f32_16x16x32_bf16 v[106:109], v[152:155], v[168:171], v[106:109]
	v_mfma_f32_16x16x32_bf16 v[94:97], v[142:145], v[176:179], v[94:97]
	v_mfma_f32_16x16x32_bf16 v[90:93], v[152:155], v[176:179], v[90:93]
	v_mfma_f32_16x16x32_bf16 v[78:81], v[142:145], v[184:187], v[78:81]
	v_mfma_f32_16x16x32_bf16 v[74:77], v[152:155], v[184:187], v[74:77]
	s_setprio 0
	s_barrier
	s_add_i32 s63, 0, 0x14000
	s_add_i32 s62, s62, s36
	v_add_u32_e32 v147, s63, v1
	v_lshl_add_u64 v[198:199], s[0:1], 0, v[130:131]
	s_mov_b32 m0, s62
	ds_read_b128 v[190:193], v147
	ds_read_b128 v[194:197], v147 offset:1024
	ds_read_b128 v[200:203], v147 offset:2048
	ds_read_b128 v[204:207], v147 offset:3072
	global_load_lds_dwordx4 v[198:199], off
	v_lshl_add_u64 v[208:209], s[0:1], 0, v[132:133]
	s_add_i32 m0, s62, 0x2000
	s_nop 0
	global_load_lds_dwordx4 v[208:209], off
	s_barrier
	s_waitcnt lgkmcnt(0)
	s_setprio 1
	s_waitcnt lgkmcnt(0)
	v_mfma_f32_16x16x32_bf16 v[118:121], v[190:193], v[156:159], v[118:121]
	v_mfma_f32_16x16x32_bf16 v[114:117], v[200:203], v[156:159], v[114:117]
	v_mfma_f32_16x16x32_bf16 v[102:105], v[190:193], v[164:167], v[102:105]
	v_mfma_f32_16x16x32_bf16 v[98:101], v[200:203], v[164:167], v[98:101]
	v_mfma_f32_16x16x32_bf16 v[86:89], v[190:193], v[172:175], v[86:89]
	v_mfma_f32_16x16x32_bf16 v[82:85], v[200:203], v[172:175], v[82:85]
	v_mfma_f32_16x16x32_bf16 v[70:73], v[190:193], v[180:183], v[70:73]
	v_mfma_f32_16x16x32_bf16 v[66:69], v[200:203], v[180:183], v[66:69]
	v_mfma_f32_16x16x32_bf16 v[118:121], v[194:197], v[160:163], v[118:121]
	v_mfma_f32_16x16x32_bf16 v[114:117], v[204:207], v[160:163], v[114:117]
	v_mfma_f32_16x16x32_bf16 v[102:105], v[194:197], v[168:171], v[102:105]
	v_mfma_f32_16x16x32_bf16 v[98:101], v[204:207], v[168:171], v[98:101]
	v_mfma_f32_16x16x32_bf16 v[86:89], v[194:197], v[176:179], v[86:89]
	v_mfma_f32_16x16x32_bf16 v[82:85], v[204:207], v[176:179], v[82:85]
	v_mfma_f32_16x16x32_bf16 v[70:73], v[194:197], v[184:187], v[70:73]
	v_mfma_f32_16x16x32_bf16 v[66:69], v[204:207], v[184:187], v[66:69]
	s_setprio 0
	s_mov_b32 m0, s37
	v_lshl_add_u64 v[210:211], s[24:25], 0, v[130:131]
	s_barrier
	ds_read_b128 v[156:159], v146 offset:16384
	ds_read_b128 v[160:163], v146 offset:17408
	ds_read_b128 v[164:167], v146 offset:18432
	ds_read_b128 v[168:171], v146 offset:19456
	ds_read_b128 v[172:175], v146 offset:20480
	ds_read_b128 v[176:179], v146 offset:21504
	ds_read_b128 v[180:183], v146 offset:22528
	ds_read_b128 v[184:187], v146 offset:23552
	global_load_lds_dwordx4 v[210:211], off
	v_lshl_add_u64 v[212:213], s[24:25], 0, v[132:133]
	s_mov_b32 m0, s38
	s_nop 0
	global_load_lds_dwordx4 v[212:213], off
	s_barrier
	s_waitcnt lgkmcnt(0)
	s_setprio 1
	s_waitcnt lgkmcnt(0)
	v_mfma_f32_16x16x32_bf16 v[62:65], v[138:141], v[156:159], v[62:65]
	v_mfma_f32_16x16x32_bf16 v[58:61], v[148:151], v[156:159], v[58:61]
	v_mfma_f32_16x16x32_bf16 v[46:49], v[138:141], v[164:167], v[46:49]
	v_mfma_f32_16x16x32_bf16 v[42:45], v[148:151], v[164:167], v[42:45]
	v_mfma_f32_16x16x32_bf16 v[30:33], v[138:141], v[172:175], v[30:33]
	v_mfma_f32_16x16x32_bf16 v[26:29], v[148:151], v[172:175], v[26:29]
	v_mfma_f32_16x16x32_bf16 v[14:17], v[138:141], v[180:183], v[14:17]
	v_mfma_f32_16x16x32_bf16 v[10:13], v[148:151], v[180:183], v[10:13]
	v_mfma_f32_16x16x32_bf16 v[62:65], v[142:145], v[160:163], v[62:65]
	v_mfma_f32_16x16x32_bf16 v[58:61], v[152:155], v[160:163], v[58:61]
	v_mfma_f32_16x16x32_bf16 v[46:49], v[142:145], v[168:171], v[46:49]
	v_mfma_f32_16x16x32_bf16 v[42:45], v[152:155], v[168:171], v[42:45]
	v_mfma_f32_16x16x32_bf16 v[30:33], v[142:145], v[176:179], v[30:33]
	v_mfma_f32_16x16x32_bf16 v[26:29], v[152:155], v[176:179], v[26:29]
	v_mfma_f32_16x16x32_bf16 v[14:17], v[142:145], v[184:187], v[14:17]
	v_mfma_f32_16x16x32_bf16 v[10:13], v[152:155], v[184:187], v[10:13]
	s_setprio 0
	s_barrier
; #define PG8_STAGE(bufoff, gbase, voff) do { _Pragma("unroll") for (int _i = 0; _i < 2; ++_i) \
;         __builtin_amdgcn_global_load_lds((const unsigned*)((const char*)(gbase) + (voff)[_i]), (LAS unsigned*)(lds + (bufoff) + ldsw + _i * 8192), 16, 0, 0); } while (0)
; #define PG8_LDA(dst, b, h) do { _Pragma("unroll") for (int m = 0; m < 4; ++m) _Pragma("unroll") for (int k = 0; k < 2; ++k) dst[m][k] = *(const LAS bf16x8*)(lds + PG8_SA(b, h) + aoff + m * 2048 + k * 1024); } while (0)
; #define PG8_LDB(dst, b, h) do { _Pragma("unroll") for (int n = 0; n < 2; ++n) _Pragma("unroll") for (int k = 0; k < 2; ++k) dst[n][k] = *(const LAS bf16x8*)(lds + PG8_SB(b, h) + boff + n * 2048 + k * 1024); } while (0)
; #define PG8_MMA(ai, bj, At, Bt) do { __builtin_amdgcn_s_setprio(1); _Pragma("unroll") for (int m = 0; m < 4; ++m) _Pragma("unroll") for (int n = 0; n < 2; ++n) _Pragma("unroll") for (int k = 0; k < 2; ++k) \
;         acc[ai][bj][m][n] = __builtin_amdgcn_mfma_f32_16x16x32_bf16(Bt[n][k], At[m][k], acc[ai][bj][m][n], 0, 0, 0); __builtin_amdgcn_s_setprio(0); } while (0)
; #define PG8_WAIT_V(n) asm volatile("s_waitcnt vmcnt(" #n ")" ::: "memory")
; #define PG8_WAIT_L(n) asm volatile("s_waitcnt lgkmcnt(" #n ")" ::: "memory")
; #define PG8_BAR __builtin_amdgcn_s_barrier()
; #define PG8_SCHED __builtin_amdgcn_sched_barrier(0)
; template <class Epi, class Sched>
; __device__ __forceinline__ void gemm_phase(LAS unsigned char* lds, const Gemm g, const Sched& S, const Epi& E) {
;     ...
;             PG8_STAGE(PG8_SB(0, 1), b2 + hstepB, voffB);
;             PG8_WAIT_V(6); PG8_BAR; PG8_MMA(1, 1, At, B1); PG8_BAR;
;             PG8_LDB(B0, 1, 0); PG8_SCHED; PG8_LDA(At, 1, 0); PG8_STAGE(PG8_SA(0, 1), a2 + hstepA, voffA);
;             PG8_WAIT_L(8); PG8_BAR; PG8_WAIT_L(0); PG8_MMA(0, 0, At, B0); PG8_BAR; PG8_SCHED;
;             PG8_LDB(B1, 1, 1); PG8_STAGE(PG8_SB(1, 0), b3, voffB);
;             PG8_BAR; PG8_WAIT_L(0); PG8_MMA(0, 1, At, B1); PG8_BAR;
;             PG8_LDA(At, 1, 1); PG8_STAGE(PG8_SA(1, 0), a3, voffA);
;             PG8_BAR; PG8_WAIT_L(0); PG8_MMA(1, 0, At, B0); PG8_BAR; PG8_SCHED;
	s_add_u32 s0, s0, s88
	s_addc_u32 s1, s1, 0
	s_add_i32 s62, s63, s36
	v_lshl_add_u64 v[214:215], s[0:1], 0, v[130:131]
	s_mov_b32 m0, s62
	v_lshl_add_u64 v[216:217], s[0:1], 0, v[132:133]
	global_load_lds_dwordx4 v[214:215], off
	s_add_i32 m0, s62, 0x2000
	s_nop 0
	global_load_lds_dwordx4 v[216:217], off
	s_waitcnt vmcnt(6)
	s_barrier
	s_setprio 1
	v_mfma_f32_16x16x32_bf16 v[54:57], v[190:193], v[156:159], v[54:57]
	v_mfma_f32_16x16x32_bf16 v[50:53], v[200:203], v[156:159], v[50:53]
	v_mfma_f32_16x16x32_bf16 v[38:41], v[190:193], v[164:167], v[38:41]
	v_mfma_f32_16x16x32_bf16 v[34:37], v[200:203], v[164:167], v[34:37]
	v_mfma_f32_16x16x32_bf16 v[22:25], v[190:193], v[172:175], v[22:25]
	v_mfma_f32_16x16x32_bf16 v[18:21], v[200:203], v[172:175], v[18:21]
	v_mfma_f32_16x16x32_bf16 v[6:9], v[190:193], v[180:183], v[6:9]
	v_mfma_f32_16x16x32_bf16 v[2:5], v[200:203], v[180:183], v[2:5]
	v_mfma_f32_16x16x32_bf16 v[54:57], v[194:197], v[160:163], v[54:57]
	v_mfma_f32_16x16x32_bf16 v[50:53], v[204:207], v[160:163], v[50:53]
	v_mfma_f32_16x16x32_bf16 v[38:41], v[194:197], v[168:171], v[38:41]
	v_mfma_f32_16x16x32_bf16 v[34:37], v[204:207], v[168:171], v[34:37]
	v_mfma_f32_16x16x32_bf16 v[22:25], v[194:197], v[176:179], v[22:25]
	v_mfma_f32_16x16x32_bf16 v[18:21], v[204:207], v[176:179], v[18:21]
	v_mfma_f32_16x16x32_bf16 v[6:9], v[194:197], v[184:187], v[6:9]
	v_mfma_f32_16x16x32_bf16 v[2:5], v[204:207], v[184:187], v[2:5]
	s_setprio 0
	s_add_i32 s62, 0, 0x18000
	v_add_u32_e32 v147, s62, v1
	s_barrier
	ds_read_b128 v[138:141], v147
	ds_read_b128 v[142:145], v147 offset:1024
	ds_read_b128 v[148:151], v147 offset:2048
	ds_read_b128 v[152:155], v147 offset:3072
	s_add_u32 s0, s24, s88
	s_addc_u32 s1, s25, 0
	s_mov_b32 m0, s39
	v_lshl_add_u64 v[190:191], s[0:1], 0, v[130:131]
	ds_read_b128 v[156:159], v146 offset:32768
	ds_read_b128 v[160:163], v146 offset:33792
	ds_read_b128 v[164:167], v146 offset:34816
	ds_read_b128 v[168:171], v146 offset:35840
	ds_read_b128 v[172:175], v146 offset:36864
	ds_read_b128 v[176:179], v146 offset:37888
	ds_read_b128 v[180:183], v146 offset:38912
	ds_read_b128 v[184:187], v146 offset:39936
	global_load_lds_dwordx4 v[190:191], off
	v_lshl_add_u64 v[190:191], s[0:1], 0, v[132:133]
	s_mov_b32 m0, s40
	s_nop 0
	global_load_lds_dwordx4 v[190:191], off
	s_waitcnt lgkmcnt(8)
	s_barrier
	s_waitcnt lgkmcnt(0)
	s_setprio 1
	s_waitcnt lgkmcnt(0)
	v_mfma_f32_16x16x32_bf16 v[126:129], v[138:141], v[156:159], v[126:129]
	v_mfma_f32_16x16x32_bf16 v[122:125], v[148:151], v[156:159], v[122:125]
	v_mfma_f32_16x16x32_bf16 v[110:113], v[138:141], v[164:167], v[110:113]
	v_mfma_f32_16x16x32_bf16 v[106:109], v[148:151], v[164:167], v[106:109]
	v_mfma_f32_16x16x32_bf16 v[94:97], v[138:141], v[172:175], v[94:97]
	v_mfma_f32_16x16x32_bf16 v[90:93], v[148:151], v[172:175], v[90:93]
	v_mfma_f32_16x16x32_bf16 v[78:81], v[138:141], v[180:183], v[78:81]
	v_mfma_f32_16x16x32_bf16 v[74:77], v[148:151], v[180:183], v[74:77]
	v_mfma_f32_16x16x32_bf16 v[126:129], v[142:145], v[160:163], v[126:129]
	v_mfma_f32_16x16x32_bf16 v[122:125], v[152:155], v[160:163], v[122:125]
	v_mfma_f32_16x16x32_bf16 v[110:113], v[142:145], v[168:171], v[110:113]
	v_mfma_f32_16x16x32_bf16 v[106:109], v[152:155], v[168:171], v[106:109]
	v_mfma_f32_16x16x32_bf16 v[94:97], v[142:145], v[176:179], v[94:97]
	v_mfma_f32_16x16x32_bf16 v[90:93], v[152:155], v[176:179], v[90:93]
	v_mfma_f32_16x16x32_bf16 v[78:81], v[142:145], v[184:187], v[78:81]
	v_mfma_f32_16x16x32_bf16 v[74:77], v[152:155], v[184:187], v[74:77]
	s_setprio 0
	s_barrier
	s_add_i32 s0, 0, 0x1c000
	s_add_i32 s1, s62, s36
	v_add_u32_e32 v147, s0, v1
	v_lshl_add_u64 v[198:199], v[198:199], 0, s[90:91]
	s_mov_b32 m0, s1
	ds_read_b128 v[190:193], v147
	ds_read_b128 v[194:197], v147 offset:1024
	ds_read_b128 v[200:203], v147 offset:2048
	ds_read_b128 v[204:207], v147 offset:3072
	global_load_lds_dwordx4 v[198:199], off
	v_lshl_add_u64 v[198:199], v[208:209], 0, s[90:91]
	s_add_i32 m0, s1, 0x2000
	s_nop 0
	global_load_lds_dwordx4 v[198:199], off
	s_barrier
	s_waitcnt lgkmcnt(0)
	s_setprio 1
	s_waitcnt lgkmcnt(0)
	v_mfma_f32_16x16x32_bf16 v[118:121], v[190:193], v[156:159], v[118:121]
	v_mfma_f32_16x16x32_bf16 v[114:117], v[200:203], v[156:159], v[114:117]
	v_mfma_f32_16x16x32_bf16 v[102:105], v[190:193], v[164:167], v[102:105]
	v_mfma_f32_16x16x32_bf16 v[98:101], v[200:203], v[164:167], v[98:101]
	v_mfma_f32_16x16x32_bf16 v[86:89], v[190:193], v[172:175], v[86:89]
	v_mfma_f32_16x16x32_bf16 v[82:85], v[200:203], v[172:175], v[82:85]
	v_mfma_f32_16x16x32_bf16 v[70:73], v[190:193], v[180:183], v[70:73]
	v_mfma_f32_16x16x32_bf16 v[66:69], v[200:203], v[180:183], v[66:69]
	v_mfma_f32_16x16x32_bf16 v[118:121], v[194:197], v[160:163], v[118:121]
	v_mfma_f32_16x16x32_bf16 v[114:117], v[204:207], v[160:163], v[114:117]
	v_mfma_f32_16x16x32_bf16 v[102:105], v[194:197], v[168:171], v[102:105]
	v_mfma_f32_16x16x32_bf16 v[98:101], v[204:207], v[168:171], v[98:101]
	v_mfma_f32_16x16x32_bf16 v[86:89], v[194:197], v[176:179], v[86:89]
	v_mfma_f32_16x16x32_bf16 v[82:85], v[204:207], v[176:179], v[82:85]
	v_mfma_f32_16x16x32_bf16 v[70:73], v[194:197], v[184:187], v[70:73]
	v_mfma_f32_16x16x32_bf16 v[66:69], v[204:207], v[184:187], v[66:69]
	s_setprio 0
	s_mov_b32 m0, s42
	v_lshl_add_u64 v[198:199], v[210:211], 0, s[90:91]
	s_barrier
	ds_read_b128 v[156:159], v146 offset:49152
	ds_read_b128 v[160:163], v146 offset:50176
	ds_read_b128 v[164:167], v146 offset:51200
	ds_read_b128 v[168:171], v146 offset:52224
	ds_read_b128 v[172:175], v146 offset:53248
	ds_read_b128 v[176:179], v146 offset:54272
	ds_read_b128 v[180:183], v146 offset:55296
	ds_read_b128 v[184:187], v146 offset:56320
	global_load_lds_dwordx4 v[198:199], off
	v_lshl_add_u64 v[198:199], v[212:213], 0, s[90:91]
	s_mov_b32 m0, s43
	s_nop 0
	global_load_lds_dwordx4 v[198:199], off
	s_barrier
; __device__ __forceinline__ int opaque_tid() { int t = threadIdx.x; asm volatile("" : "+v"(t)); return t; }
; #define PG8_STAGE(bufoff, gbase, voff) do { _Pragma("unroll") for (int _i = 0; _i < 2; ++_i) \
;         __builtin_amdgcn_global_load_lds((const unsigned*)((const char*)(gbase) + (voff)[_i]), (LAS unsigned*)(lds + (bufoff) + ldsw + _i * 8192), 16, 0, 0); } while (0)
; #define PG8_MMA(ai, bj, At, Bt) do { __builtin_amdgcn_s_setprio(1); _Pragma("unroll") for (int m = 0; m < 4; ++m) _Pragma("unroll") for (int n = 0; n < 2; ++n) _Pragma("unroll") for (int k = 0; k < 2; ++k) \
;         acc[ai][bj][m][n] = __builtin_amdgcn_mfma_f32_16x16x32_bf16(Bt[n][k], At[m][k], acc[ai][bj][m][n], 0, 0, 0); __builtin_amdgcn_s_setprio(0); } while (0)
; #define PG8_WAIT_V(n) asm volatile("s_waitcnt vmcnt(" #n ")" ::: "memory")
; #define PG8_BAR __builtin_amdgcn_s_barrier()
; template <class Epi, class Sched>
; __device__ __forceinline__ void gemm_phase(LAS unsigned char* lds, const Gemm g, const Sched& S, const Epi& E) {
;     ...
;             PG8_BAR; PG8_WAIT_L(0); PG8_MMA(1, 0, At, B0); PG8_BAR; PG8_SCHED;
;             PG8_STAGE(PG8_SB(1, 1), b3 + hstepB, voffB);
;             PG8_WAIT_V(6); PG8_BAR; PG8_MMA(1, 1, At, B1); PG8_BAR;
;     __device__ __forceinline__ void operator()(const f32x4 (&acc)[2][2][4][2], const Unit& u, int wr, int wc, int fr, int fq) const {
;         { const int t_ = opaque_tid(); wr = t_ >> 8; wc = (t_ >> 6) & 3; fr = t_ & 15; fq = (t_ >> 4) & 3; }
;         const int row0 = u.pm * 256 + wr * 64 + fr, col0 = u.pn * 256 + wc * 32 + 4 * fq;
; #pragma unroll
;         for (int ai = 0; ai < 2; ++ai)
; #pragma unroll
;             for (int m = 0; m < 4; ++m) {
;                 const int row = row0 + ai * 128 + m * 16;
;                 float* hp = row < RL ? Hl + (size_t)row * 1024 : Hc + (size_t)(row - RL) * 1024;
;                 const float* gp = gate + (row < RL ? (row >> 13) : 4) * 9216;
; #pragma unroll
;                 for (int bj = 0; bj < 2; ++bj)
; #pragma unroll
;                     for (int n = 0; n < 2; ++n) {
;                         const int c = col0 + bj * 128 + n * 16;
;                         const f32x4 g4 = *(const f32x4*)(gp + c); f32x4 h4 = *(const f32x4*)(hp + c);
;                         h4 += (g4 * coef) * acc[ai][bj][m][n];
;                         *(f32x4*)(hp + c) = h4;
;                     }
	s_waitcnt lgkmcnt(0)
	s_setprio 1
	s_waitcnt lgkmcnt(0)
	v_mfma_f32_16x16x32_bf16 v[62:65], v[138:141], v[156:159], v[62:65]
	v_mfma_f32_16x16x32_bf16 v[58:61], v[148:151], v[156:159], v[58:61]
	v_mfma_f32_16x16x32_bf16 v[46:49], v[138:141], v[164:167], v[46:49]
	v_mfma_f32_16x16x32_bf16 v[42:45], v[148:151], v[164:167], v[42:45]
	v_mfma_f32_16x16x32_bf16 v[30:33], v[138:141], v[172:175], v[30:33]
	v_mfma_f32_16x16x32_bf16 v[26:29], v[148:151], v[172:175], v[26:29]
	v_mfma_f32_16x16x32_bf16 v[14:17], v[138:141], v[180:183], v[14:17]
	v_mfma_f32_16x16x32_bf16 v[10:13], v[148:151], v[180:183], v[10:13]
	v_mfma_f32_16x16x32_bf16 v[62:65], v[142:145], v[160:163], v[62:65]
	v_mfma_f32_16x16x32_bf16 v[58:61], v[152:155], v[160:163], v[58:61]
	v_mfma_f32_16x16x32_bf16 v[46:49], v[142:145], v[168:171], v[46:49]
	v_mfma_f32_16x16x32_bf16 v[42:45], v[152:155], v[168:171], v[42:45]
	v_mfma_f32_16x16x32_bf16 v[30:33], v[142:145], v[176:179], v[30:33]
	v_mfma_f32_16x16x32_bf16 v[26:29], v[152:155], v[176:179], v[26:29]
	v_mfma_f32_16x16x32_bf16 v[14:17], v[142:145], v[184:187], v[14:17]
	v_mfma_f32_16x16x32_bf16 v[10:13], v[152:155], v[184:187], v[10:13]
	s_setprio 0
	s_barrier
	s_add_i32 s0, s0, s36
	v_lshl_add_u64 v[138:139], v[214:215], 0, s[90:91]
	s_mov_b32 m0, s0
	s_nop 0
	global_load_lds_dwordx4 v[138:139], off
	v_lshl_add_u64 v[138:139], v[216:217], 0, s[90:91]
	s_add_i32 m0, s0, 0x2000
	s_nop 0
	global_load_lds_dwordx4 v[138:139], off
	s_waitcnt vmcnt(6)
	s_barrier
	s_setprio 1
	v_mfma_f32_16x16x32_bf16 v[54:57], v[190:193], v[156:159], v[54:57]
	v_mfma_f32_16x16x32_bf16 v[50:53], v[200:203], v[156:159], v[50:53]
	v_mfma_f32_16x16x32_bf16 v[38:41], v[190:193], v[164:167], v[38:41]
	v_mfma_f32_16x16x32_bf16 v[34:37], v[200:203], v[164:167], v[34:37]
	v_mfma_f32_16x16x32_bf16 v[22:25], v[190:193], v[172:175], v[22:25]
	v_mfma_f32_16x16x32_bf16 v[18:21], v[200:203], v[172:175], v[18:21]
	v_mfma_f32_16x16x32_bf16 v[6:9], v[190:193], v[180:183], v[6:9]
	v_mfma_f32_16x16x32_bf16 v[2:5], v[200:203], v[180:183], v[2:5]
	v_mfma_f32_16x16x32_bf16 v[54:57], v[194:197], v[160:163], v[54:57]
	v_mfma_f32_16x16x32_bf16 v[50:53], v[204:207], v[160:163], v[50:53]
	v_mfma_f32_16x16x32_bf16 v[38:41], v[194:197], v[168:171], v[38:41]
	v_mfma_f32_16x16x32_bf16 v[34:37], v[204:207], v[168:171], v[34:37]
	v_mfma_f32_16x16x32_bf16 v[22:25], v[194:197], v[176:179], v[22:25]
	v_mfma_f32_16x16x32_bf16 v[18:21], v[204:207], v[176:179], v[18:21]
	v_mfma_f32_16x16x32_bf16 v[6:9], v[194:197], v[184:187], v[6:9]
	v_mfma_f32_16x16x32_bf16 v[2:5], v[204:207], v[184:187], v[2:5]
	s_setprio 0
	s_add_u32 s59, s59, 0x100
	s_addc_u32 s60, s60, 0
	s_add_u32 s2, s2, 0x100
	s_addc_u32 s3, s3, 0
	s_cmp_ge_u32 s61, s41
	s_mov_b32 s0, s61
	s_barrier
	s_cbranch_scc0 .LBB0_567
	v_mov_b32_e32 v147, v189
	s_lshl_b32 s0, s58, 8
	v_ashrrev_i32_e32 v138, 2, v147
	v_and_b32_e32 v138, 0xffffffc0, v138
	v_and_or_b32 v139, v147, 15, s0
	v_add_u32_e32 v138, v139, v138
	v_lshrrev_b32_e32 v148, 1, v147
	v_lshrrev_b32_e32 v147, 2, v147
	s_lshl_b32 s0, s13, 8
	v_and_b32_e32 v148, 0x60, v148
	v_and_b32_e32 v147, 12, v147
	v_or3_b32 v148, v148, s0, v147
	v_lshlrev_b32_e32 v140, 2, v148
	s_mov_b32 s13, s12
	v_readlane_b32 s63, v255, 2
	s_lshr_b32 s2, s58, 5
	s_mul_i32 s2, s2, 0x9000
	s_cmp_gt_u32 s58, 0x7f
	s_cselect_b32 s2, 0x24000, s2
	s_cselect_b32 s0, s22, s16
	s_cselect_b32 s1, s23, s17
	s_cselect_b32 s3, 0x8000, 0
	v_add_u32_e32 v147, s2, v140
	v_subrev_u32_e32 v138, s3, v138
	v_lshl_add_u32 v138, v138, 12, v140
	v_add_u32_e32 v145, 0xb0000, v138
	v_add_u32_e32 v144, 0xa0000, v138
	v_add_u32_e32 v143, 0x90000, v138
	v_add_u32_e32 v142, 0x80000, v138
	v_add_u32_e32 v141, 0x30000, v138
	v_add_u32_e32 v140, 0x20000, v138
	v_add_u32_e32 v139, 0x10000, v138
	global_load_dwordx4 v[148:151], v147, s[18:19]
	global_load_dwordx4 v[152:155], v147, s[18:19] offset:64
	global_load_dwordx4 v[156:159], v147, s[18:19] offset:512
	global_load_dwordx4 v[160:163], v147, s[18:19] offset:576
	global_load_dwordx4 v[164:167], v138, s[0:1]
	global_load_dwordx4 v[168:171], v138, s[0:1] offset:64
	global_load_dwordx4 v[172:175], v138, s[0:1] offset:512
	global_load_dwordx4 v[176:179], v138, s[0:1] offset:576
	global_load_dwordx4 v[180:183], v139, s[0:1]
	global_load_dwordx4 v[184:187], v139, s[0:1] offset:64
	global_load_dwordx4 v[190:193], v139, s[0:1] offset:512
	global_load_dwordx4 v[194:197], v139, s[0:1] offset:576
	global_load_dwordx4 v[200:203], v140, s[0:1]
	global_load_dwordx4 v[204:207], v140, s[0:1] offset:64
	global_load_dwordx4 v[222:225], v140, s[0:1] offset:512
	global_load_dwordx4 v[226:229], v140, s[0:1] offset:576
	global_load_dwordx4 v[232:235], v141, s[0:1]
	global_load_dwordx4 v[236:239], v141, s[0:1] offset:64
	global_load_dwordx4 v[246:249], v141, s[0:1] offset:512
	global_load_dwordx4 v[250:253], v141, s[0:1] offset:576
	s_waitcnt vmcnt(16)
	v_pk_mul_f32 v[150:151], s[12:13], v[150:151]
	v_pk_mul_f32 v[148:149], s[14:15], v[148:149]
	v_pk_mul_f32 v[154:155], s[12:13], v[154:155]
	v_pk_mul_f32 v[152:153], s[14:15], v[152:153]
	v_pk_mul_f32 v[158:159], s[12:13], v[158:159]
	v_pk_mul_f32 v[156:157], s[14:15], v[156:157]
	v_pk_mul_f32 v[162:163], s[12:13], v[162:163]
	v_pk_mul_f32 v[160:161], s[14:15], v[160:161]
	s_waitcnt vmcnt(15)
	v_pk_fma_f32 v[166:167], v[128:129], v[150:151], v[166:167]
	v_pk_fma_f32 v[164:165], v[126:127], v[148:149], v[164:165]
	global_store_dwordx4 v138, v[164:167], s[0:1]
	s_waitcnt vmcnt(15)
	v_pk_fma_f32 v[170:171], v[124:125], v[154:155], v[170:171]
	v_pk_fma_f32 v[168:169], v[122:123], v[152:153], v[168:169]
	global_store_dwordx4 v138, v[168:171], s[0:1] offset:64
	s_waitcnt vmcnt(15)
;     __device__ __forceinline__ void operator()(const f32x4 (&acc)[2][2][4][2], const Unit& u, int wr, int wc, int fr, int fq) const {
;     ...
;             for (int m = 0; m < 4; ++m) {
;                 const int row = row0 + ai * 128 + m * 16;
;                 float* hp = row < RL ? Hl + (size_t)row * 1024 : Hc + (size_t)(row - RL) * 1024;
;                 const float* gp = gate + (row < RL ? (row >> 13) : 4) * 9216;
; #pragma unroll
;                 for (int bj = 0; bj < 2; ++bj)
; #pragma unroll
;                     for (int n = 0; n < 2; ++n) {
;                         const int c = col0 + bj * 128 + n * 16;
;                         const f32x4 g4 = *(const f32x4*)(gp + c); f32x4 h4 = *(const f32x4*)(hp + c);
;                         h4 += (g4 * coef) * acc[ai][bj][m][n];
;                         *(f32x4*)(hp + c) = h4;
;                     }
	v_pk_fma_f32 v[174:175], v[120:121], v[158:159], v[174:175]
	v_pk_fma_f32 v[172:173], v[118:119], v[156:157], v[172:173]
	global_store_dwordx4 v138, v[172:175], s[0:1] offset:512
	s_waitcnt vmcnt(15)
	v_pk_fma_f32 v[178:179], v[116:117], v[162:163], v[178:179]
	v_pk_fma_f32 v[176:177], v[114:115], v[160:161], v[176:177]
	global_store_dwordx4 v138, v[176:179], s[0:1] offset:576
	global_load_dwordx4 v[126:129], v142, s[0:1]
	global_load_dwordx4 v[122:125], v142, s[0:1] offset:64
	global_load_dwordx4 v[118:121], v142, s[0:1] offset:512
	global_load_dwordx4 v[114:117], v142, s[0:1] offset:576
	s_waitcnt vmcnt(19)
	v_pk_fma_f32 v[182:183], v[112:113], v[150:151], v[182:183]
	v_pk_fma_f32 v[180:181], v[110:111], v[148:149], v[180:181]
	global_store_dwordx4 v139, v[180:183], s[0:1]
	s_waitcnt vmcnt(19)
	v_pk_fma_f32 v[186:187], v[108:109], v[154:155], v[186:187]
	v_pk_fma_f32 v[184:185], v[106:107], v[152:153], v[184:185]
	global_store_dwordx4 v139, v[184:187], s[0:1] offset:64
	s_waitcnt vmcnt(19)
	v_pk_fma_f32 v[192:193], v[104:105], v[158:159], v[192:193]
	v_pk_fma_f32 v[190:191], v[102:103], v[156:157], v[190:191]
	global_store_dwordx4 v139, v[190:193], s[0:1] offset:512
	s_waitcnt vmcnt(19)
	v_pk_fma_f32 v[196:197], v[100:101], v[162:163], v[196:197]
	v_pk_fma_f32 v[194:195], v[98:99], v[160:161], v[194:195]
	global_store_dwordx4 v139, v[194:197], s[0:1] offset:576
	global_load_dwordx4 v[110:113], v143, s[0:1]
	global_load_dwordx4 v[106:109], v143, s[0:1] offset:64
	global_load_dwordx4 v[102:105], v143, s[0:1] offset:512
	global_load_dwordx4 v[98:101], v143, s[0:1] offset:576
	s_waitcnt vmcnt(23)
	v_pk_fma_f32 v[202:203], v[96:97], v[150:151], v[202:203]
	v_pk_fma_f32 v[200:201], v[94:95], v[148:149], v[200:201]
	global_store_dwordx4 v140, v[200:203], s[0:1]
	s_waitcnt vmcnt(23)
	v_pk_fma_f32 v[206:207], v[92:93], v[154:155], v[206:207]
	v_pk_fma_f32 v[204:205], v[90:91], v[152:153], v[204:205]
	global_store_dwordx4 v140, v[204:207], s[0:1] offset:64
	s_waitcnt vmcnt(23)
	v_pk_fma_f32 v[224:225], v[88:89], v[158:159], v[224:225]
	v_pk_fma_f32 v[222:223], v[86:87], v[156:157], v[222:223]
	global_store_dwordx4 v140, v[222:225], s[0:1] offset:512
	s_waitcnt vmcnt(23)
	v_pk_fma_f32 v[228:229], v[84:85], v[162:163], v[228:229]
	v_pk_fma_f32 v[226:227], v[82:83], v[160:161], v[226:227]
	global_store_dwordx4 v140, v[226:229], s[0:1] offset:576
	global_load_dwordx4 v[94:97], v144, s[0:1]
	global_load_dwordx4 v[90:93], v144, s[0:1] offset:64
	global_load_dwordx4 v[86:89], v144, s[0:1] offset:512
	global_load_dwordx4 v[82:85], v144, s[0:1] offset:576
	s_waitcnt vmcnt(27)
	v_pk_fma_f32 v[234:235], v[80:81], v[150:151], v[234:235]
	v_pk_fma_f32 v[232:233], v[78:79], v[148:149], v[232:233]
	global_store_dwordx4 v141, v[232:235], s[0:1]
	s_waitcnt vmcnt(27)
	v_pk_fma_f32 v[238:239], v[76:77], v[154:155], v[238:239]
	v_pk_fma_f32 v[236:237], v[74:75], v[152:153], v[236:237]
	global_store_dwordx4 v141, v[236:239], s[0:1] offset:64
	s_waitcnt vmcnt(27)
	v_pk_fma_f32 v[248:249], v[72:73], v[158:159], v[248:249]
	v_pk_fma_f32 v[246:247], v[70:71], v[156:157], v[246:247]
	global_store_dwordx4 v141, v[246:249], s[0:1] offset:512
	s_waitcnt vmcnt(27)
	v_pk_fma_f32 v[252:253], v[68:69], v[162:163], v[252:253]
	v_pk_fma_f32 v[250:251], v[66:67], v[160:161], v[250:251]
	global_store_dwordx4 v141, v[250:253], s[0:1] offset:576
	global_load_dwordx4 v[78:81], v145, s[0:1]
	global_load_dwordx4 v[74:77], v145, s[0:1] offset:64
	global_load_dwordx4 v[70:73], v145, s[0:1] offset:512
	global_load_dwordx4 v[66:69], v145, s[0:1] offset:576
	s_waitcnt vmcnt(27)
	v_pk_fma_f32 v[128:129], v[64:65], v[150:151], v[128:129]
	v_pk_fma_f32 v[126:127], v[62:63], v[148:149], v[126:127]
	global_store_dwordx4 v142, v[126:129], s[0:1]
	s_waitcnt vmcnt(27)
	v_pk_fma_f32 v[124:125], v[60:61], v[154:155], v[124:125]
	v_pk_fma_f32 v[122:123], v[58:59], v[152:153], v[122:123]
	global_store_dwordx4 v142, v[122:125], s[0:1] offset:64
	s_waitcnt vmcnt(27)
	v_pk_fma_f32 v[120:121], v[56:57], v[158:159], v[120:121]
	v_pk_fma_f32 v[118:119], v[54:55], v[156:157], v[118:119]
	global_store_dwordx4 v142, v[118:121], s[0:1] offset:512
	s_waitcnt vmcnt(27)
	v_pk_fma_f32 v[116:117], v[52:53], v[162:163], v[116:117]
	v_pk_fma_f32 v[114:115], v[50:51], v[160:161], v[114:115]
	global_store_dwordx4 v142, v[114:117], s[0:1] offset:576
	s_waitcnt vmcnt(23)
	v_pk_fma_f32 v[112:113], v[48:49], v[150:151], v[112:113]
	v_pk_fma_f32 v[110:111], v[46:47], v[148:149], v[110:111]
	global_store_dwordx4 v143, v[110:113], s[0:1]
	s_waitcnt vmcnt(23)
	v_pk_fma_f32 v[108:109], v[44:45], v[154:155], v[108:109]
	v_pk_fma_f32 v[106:107], v[42:43], v[152:153], v[106:107]
	global_store_dwordx4 v143, v[106:109], s[0:1] offset:64
	s_waitcnt vmcnt(23)
	v_pk_fma_f32 v[104:105], v[40:41], v[158:159], v[104:105]
	v_pk_fma_f32 v[102:103], v[38:39], v[156:157], v[102:103]
	global_store_dwordx4 v143, v[102:105], s[0:1] offset:512
	s_waitcnt vmcnt(23)
	v_pk_fma_f32 v[100:101], v[36:37], v[162:163], v[100:101]
	v_pk_fma_f32 v[98:99], v[34:35], v[160:161], v[98:99]
	global_store_dwordx4 v143, v[98:101], s[0:1] offset:576
	s_waitcnt vmcnt(19)
	v_pk_fma_f32 v[96:97], v[32:33], v[150:151], v[96:97]
	v_pk_fma_f32 v[94:95], v[30:31], v[148:149], v[94:95]
	global_store_dwordx4 v144, v[94:97], s[0:1]
	s_waitcnt vmcnt(19)
	v_pk_fma_f32 v[92:93], v[28:29], v[154:155], v[92:93]
	v_pk_fma_f32 v[90:91], v[26:27], v[152:153], v[90:91]
	global_store_dwordx4 v144, v[90:93], s[0:1] offset:64
	s_waitcnt vmcnt(19)
	v_pk_fma_f32 v[88:89], v[24:25], v[158:159], v[88:89]
	v_pk_fma_f32 v[86:87], v[22:23], v[156:157], v[86:87]
	global_store_dwordx4 v144, v[86:89], s[0:1] offset:512
	s_waitcnt vmcnt(19)
	v_pk_fma_f32 v[84:85], v[20:21], v[162:163], v[84:85]
	v_pk_fma_f32 v[82:83], v[18:19], v[160:161], v[82:83]
	global_store_dwordx4 v144, v[82:85], s[0:1] offset:576
	s_waitcnt vmcnt(15)
	v_pk_fma_f32 v[80:81], v[16:17], v[150:151], v[80:81]
	v_pk_fma_f32 v[78:79], v[14:15], v[148:149], v[78:79]
	global_store_dwordx4 v145, v[78:81], s[0:1]
	s_waitcnt vmcnt(15)
	v_pk_fma_f32 v[76:77], v[12:13], v[154:155], v[76:77]
	v_pk_fma_f32 v[74:75], v[10:11], v[152:153], v[74:75]
	global_store_dwordx4 v145, v[74:77], s[0:1] offset:64
	s_waitcnt vmcnt(15)
	v_pk_fma_f32 v[72:73], v[8:9], v[158:159], v[72:73]
	v_pk_fma_f32 v[70:71], v[6:7], v[156:157], v[70:71]
	global_store_dwordx4 v145, v[70:73], s[0:1] offset:512
	s_waitcnt vmcnt(15)
	v_pk_fma_f32 v[68:69], v[4:5], v[162:163], v[68:69]
	v_pk_fma_f32 v[66:67], v[2:3], v[160:161], v[66:67]
	global_store_dwordx4 v145, v[66:69], s[0:1] offset:576
	s_branch .LBB0_555
